# GB3: barriers after out-proj and after LN become 64-workgroup band barriers (LN rows remapped band-local); L2 writeback skipped only when a run-time census shows the band's workgroups share one XCC
# speedup vs baseline: 1.0050x; 1.0050x over previous
.LBB0_2:
	s_or_b64 exec, exec, s[6:7]
	s_waitcnt lgkmcnt(0)
	s_barrier
	s_add_u32 s8, s80, 0x4000
	s_getreg_b32 s3, hwreg(HW_REG_XCC_ID, 0, 4)
	s_addc_u32 s9, s81, 0
	s_and_b32 s33, s3, 15
	s_mov_b64 s[6:7], exec
	v_readlane_b32 s10, v234, 0
	v_readlane_b32 s11, v234, 1
	s_and_b64 s[10:11], s[6:7], s[10:11]
	s_mov_b64 exec, s[10:11]
	s_cbranch_execz .LBB0_5
	s_mov_b64 s[10:11], exec
	v_mbcnt_lo_u32_b32 v1, s10, 0
	v_mbcnt_hi_u32_b32 v1, s11, v1
	v_cmp_eq_u32_e32 vcc, 0, v1
	s_and_b64 s[12:13], exec, vcc
	s_mov_b64 exec, s[12:13]
	s_cbranch_execz .LBB0_5
	s_lshl_b32 s3, s33, 8
	s_bcnt1_i32_b64 s10, s[10:11]
	v_mov_b32_e32 v1, s3
	v_mov_b32_e32 v2, s10
	global_atomic_add v1, v2, s[8:9] offset:1024
	s_and_b32 s10, s74, 7
	s_lshl_b32 s10, s10, 8
	s_add_u32 s10, s10, 0xc40
	s_lshl_b32 s11, 1, s33
	v_mov_b32_e32 v1, s10
	v_mov_b32_e32 v2, s11
	global_atomic_or v1, v2, s[8:9]

.LBB0_167:
	s_or_b64 exec, exec, s[0:1]
	s_add_u32 s48, s80, 0x1a00000
	s_addc_u32 s49, s81, 0
	s_add_u32 s0, s80, 0x400000
	v_writelane_b32 v234, s0, 40
	s_addc_u32 s0, s81, 0
	v_writelane_b32 v234, s0, 41
	s_and_b32 s0, s60, 7
	s_cmp_lg_u32 s0, 0
	s_cselect_b64 s[0:1], -1, 0
	s_cmp_lt_i32 s60, 8
	s_cselect_b64 s[4:5], -1, 0
	s_or_b64 s[28:29], s[4:5], s[0:1]
	s_lshl_b32 s0, s74, 4
	s_lshr_b32 s50, s74, 3
	s_lshr_b32 s51, s60, 3
	s_and_b32 s52, s0, 0x70
	s_add_u32 s0, s80, 0xca00000
	s_addc_u32 s1, s81, 0
	v_writelane_b32 v234, s0, 42
	v_lshl_add_u64 v[0:1], v[0:1], 2, s[8:9]
	s_nop 0
	v_writelane_b32 v234, s1, 43
	s_add_u32 s0, s80, 0xc200000
	s_addc_u32 s1, s81, 0
	v_writelane_b32 v234, s0, 44
	s_barrier
	s_nop 0
	v_writelane_b32 v234, s1, 45
	s_add_u32 s0, s80, 0xba00000
	s_addc_u32 s1, s81, 0
	v_writelane_b32 v234, s0, 46
	s_mov_b32 s87, 0
	v_mov_b32_e32 v157, 0x3ecc95a3
	v_writelane_b32 v234, s1, 47
	s_add_u32 s0, s80, 0xb600000
	s_addc_u32 s1, s81, 0
	v_writelane_b32 v234, s0, 48
	v_mov_b32_e32 v158, 0x12010
	v_mov_b32_e32 v159, 0x12014
	v_writelane_b32 v234, s1, 49
	s_add_u32 s0, s80, 0xb200000
	s_addc_u32 s1, s81, 0
	v_writelane_b32 v234, s0, 50
	v_mov_b32_e32 v160, 1
	v_mov_b32_e32 v161, 0x12000
	v_writelane_b32 v234, s1, 51
	s_add_u32 s0, s80, 0xae00000
	s_addc_u32 s1, s81, 0
	v_writelane_b32 v234, s0, 52
	v_mov_b32_e32 v162, 0x3727c5ac
	v_mov_b32_e32 v163, 0x4000
	v_writelane_b32 v234, s1, 53
	s_add_u32 s0, s80, 0xaa00000
	s_addc_u32 s1, s81, 0
	v_writelane_b32 v234, s0, 54
	v_mov_b32_e32 v164, 0x7f
	v_mov_b32_e32 v165, 0xfffff500
	v_writelane_b32 v234, s1, 55
	s_add_u32 s0, s80, 0xa600000
	s_addc_u32 s1, s81, 0
	v_writelane_b32 v234, s0, 56
	v_mov_b32_e32 v166, 0xfffff800
	v_mov_b32_e32 v167, 0xfffffd00
	v_writelane_b32 v234, s1, 57
	s_add_u32 s0, s80, 0xa200000
	s_addc_u32 s1, s81, 0
	v_writelane_b32 v234, s0, 58
	v_mov_b32_e32 v168, 0x7f800000
	v_mov_b32_e32 v124, 0x3f317218
	v_writelane_b32 v234, s1, 59
	s_add_u32 s0, s80, 0x9200000
	s_addc_u32 s1, s81, 0
	s_add_u32 s54, s80, 0x8a00000
	s_addc_u32 s55, s81, 0
	s_add_u32 s58, s80, 0x8200000
	s_addc_u32 s59, s81, 0
	s_add_u32 s62, s80, 0x7a00000
	v_writelane_b32 v234, s0, 60
	s_addc_u32 s63, s81, 0
	v_mov_b32_e32 v169, 0xf149f2ca
	v_writelane_b32 v234, s1, 61
	s_add_u32 s0, s80, 0xd200000
	s_addc_u32 s1, s81, 0
	v_writelane_b32 v234, s0, 62
	v_mov_b32_e32 v171, 0x80
	v_mov_b32_e32 v172, 0x100
	v_writelane_b32 v234, s1, 63
	s_add_u32 s0, s80, 0x3a00000
	s_addc_u32 s1, s81, 0
	s_add_u32 s26, s80, 0x4200
	s_addc_u32 s27, s81, 0
	s_add_u32 s38, s80, 0x4400
	s_addc_u32 s39, s81, 0
	s_add_u32 s44, s80, 0x4500
	s_addc_u32 s45, s81, 0
	s_add_u32 s56, s80, 0x4600
	v_writelane_b32 v233, s0, 0
	s_addc_u32 s57, s81, 0
	v_mov_b32_e32 v173, 0x200
	v_writelane_b32 v233, s1, 1
	s_add_u32 s0, s80, 0x4700
	s_addc_u32 s1, s81, 0
	v_writelane_b32 v233, s0, 2
	v_mov_b32_e32 v174, 0x400
	v_mov_b32_e32 v175, 0x800
	v_writelane_b32 v233, s1, 3
	s_add_u32 s0, s80, 0x4800
	s_addc_u32 s1, s81, 0
	v_writelane_b32 v233, s0, 4
	v_mov_b32_e32 v176, 0x1000
	v_mov_b32_e32 v177, 0x2000
	v_writelane_b32 v233, s1, 5
	s_add_u32 s0, s80, 0x4900
	s_addc_u32 s1, s81, 0
	v_writelane_b32 v233, s0, 6
	v_mov_b32_e32 v178, 0x8000
	v_mov_b32_e32 v179, 0x11e00
	v_writelane_b32 v233, s1, 7
	s_add_u32 s0, s80, 0x4a00
	s_addc_u32 s1, s81, 0
	v_writelane_b32 v233, s0, 8
	v_mov_b64_e32 v[126:127], 0x7f
	s_movk_i32 s19, 0x70
	v_writelane_b32 v233, s1, 9
	s_add_u32 s0, s80, 0x4b00
	s_addc_u32 s1, s81, 0
	v_writelane_b32 v233, s0, 10
	s_movk_i32 s71, 0x7fff
	s_mov_b32 s20, 0x53800000
	v_writelane_b32 v233, s1, 11
	s_add_u32 s0, s80, 0x4c00
	s_addc_u32 s1, s81, 0
	v_writelane_b32 v233, s0, 12
	s_mov_b32 s21, 0x4a800000
	s_mov_b64 s[30:31], 0x7f
	v_writelane_b32 v233, s1, 13
	s_add_u32 s0, s80, 0x4d00
	s_addc_u32 s1, s81, 0
	v_writelane_b32 v233, s0, 14
	s_mov_b64 s[64:65], 0x1a00080
	s_mov_b64 s[66:67], 0x400080
	v_writelane_b32 v233, s1, 15
	s_add_u32 s0, s80, 0x4e00
	s_addc_u32 s1, s81, 0
	v_writelane_b32 v233, s0, 16
	s_mov_b64 s[68:69], 0x1a00100
	s_mov_b64 s[40:41], 0x400100
	v_writelane_b32 v233, s1, 17
	s_add_u32 s0, s80, 0x4f00
	s_addc_u32 s1, s81, 0
	v_writelane_b32 v233, s0, 18
	s_mov_b64 s[36:37], 0x100
	s_mov_b64 s[34:35], 0x80
	v_writelane_b32 v233, s1, 19
	s_add_u32 s0, s80, 0x5000
	s_addc_u32 s1, s81, 0
	v_writelane_b32 v233, s0, 20
	s_mov_b64 s[42:43], 0x1800080
	s_mov_b64 s[46:47], 0x1800100
	v_writelane_b32 v233, s1, 21
	s_add_u32 s0, s80, 0x5100
	s_addc_u32 s1, s81, 0
	v_writelane_b32 v233, s0, 22
	s_mov_b64 s[88:89], 0x5a00080
	s_mov_b64 s[90:91], 0x1400080
	v_writelane_b32 v233, s1, 23
	s_add_u32 s0, s80, 0x5200
	s_addc_u32 s1, s81, 0
	v_writelane_b32 v233, s0, 24
	s_mov_b64 s[94:95], 0x5a00100
	s_mov_b64 s[96:97], 0x1400100
	v_writelane_b32 v233, s1, 25
	s_add_u32 s0, s80, 0x5300
	s_addc_u32 s1, s81, 0
	v_writelane_b32 v233, s0, 26
	s_cmp_eq_u32 s33, 15
	s_mov_b32 s70, 0x3fb504f3
	v_writelane_b32 v233, s1, 27
	s_cselect_b64 s[0:1], -1, 0
	v_writelane_b32 v233, s0, 28
	s_cmp_eq_u32 s33, 14
	s_mov_b32 s2, s87
	v_writelane_b32 v233, s1, 29
	s_cselect_b64 s[0:1], -1, 0
	v_writelane_b32 v233, s0, 30
	s_cmp_eq_u32 s33, 13
	s_nop 0
	v_writelane_b32 v233, s1, 31
	s_cselect_b64 s[0:1], -1, 0
	v_writelane_b32 v233, s0, 32
	s_cmp_eq_u32 s33, 12
	s_nop 0
	v_writelane_b32 v233, s1, 33
	s_mov_b64 s[0:1], 0x1400
	v_lshl_add_u64 v[120:121], v[0:1], 0, s[0:1]
	s_mov_b64 s[0:1], 0x2400
	v_lshl_add_u64 v[122:123], v[0:1], 0, s[0:1]
	s_cselect_b64 s[0:1], -1, 0
	v_writelane_b32 v233, s0, 34
	s_cmp_eq_u32 s33, 11
	v_mov_b32_e32 v1, 0
	v_writelane_b32 v233, s1, 35
	s_cselect_b64 s[0:1], -1, 0
	v_writelane_b32 v233, s0, 36
	s_cmp_eq_u32 s33, 10
	v_mbcnt_lo_u32_b32 v0, -1, 0
	v_writelane_b32 v233, s1, 37
	s_cselect_b64 s[0:1], -1, 0
	v_writelane_b32 v233, s0, 38
	s_cmp_eq_u32 s33, 9
	v_mbcnt_hi_u32_b32 v170, -1, v0
	v_writelane_b32 v233, s1, 39
	s_cselect_b64 s[0:1], -1, 0
	v_writelane_b32 v233, s0, 40
	s_cmp_eq_u32 s33, 8
	s_nop 0
	v_writelane_b32 v233, s1, 41
	s_cselect_b64 s[0:1], -1, 0
	v_writelane_b32 v233, s0, 42
	s_cmp_eq_u32 s33, 7
	s_nop 0
	v_writelane_b32 v233, s1, 43
	s_cselect_b64 s[0:1], -1, 0
	v_writelane_b32 v233, s0, 44
	s_cmp_eq_u32 s33, 6
	s_nop 0
	v_writelane_b32 v233, s1, 45
	s_cselect_b64 s[0:1], -1, 0
	v_writelane_b32 v233, s0, 46
	s_cmp_eq_u32 s33, 5
	s_nop 0
	v_writelane_b32 v233, s1, 47
	s_cselect_b64 s[0:1], -1, 0
	v_writelane_b32 v233, s0, 48
	s_cmp_eq_u32 s33, 4
	s_nop 0
	v_writelane_b32 v233, s1, 49
	s_cselect_b64 s[0:1], -1, 0
	v_writelane_b32 v233, s0, 50
	s_cmp_eq_u32 s33, 3
	s_nop 0
	v_writelane_b32 v233, s1, 51
	s_cselect_b64 s[0:1], -1, 0
	v_writelane_b32 v233, s0, 52
	s_cmp_eq_u32 s33, 2
	s_nop 0
	v_writelane_b32 v233, s1, 53
	s_cselect_b64 s[0:1], -1, 0
	v_writelane_b32 v233, s0, 54
	s_cmp_eq_u32 s33, 1
	s_nop 0
	v_writelane_b32 v233, s1, 55
	s_cselect_b64 s[0:1], -1, 0
	v_writelane_b32 v233, s0, 56
	s_cmp_eq_u32 s33, 0
	s_movk_i32 s33, 0x2400
	v_writelane_b32 v233, s1, 57
	s_cselect_b64 s[0:1], -1, 0
	v_writelane_b32 v233, s0, 58
	s_nop 1
	v_writelane_b32 v233, s1, 59
	s_add_u32 s0, s80, 0x7400
	s_addc_u32 s1, s81, 0
	v_writelane_b32 v233, s0, 60
	s_nop 1
	v_writelane_b32 v233, s1, 61
	s_add_u32 s0, s80, 0x7500
	s_addc_u32 s1, s81, 0
	s_add_u32 s53, s80, 0xd240000
	s_addc_u32 s61, s81, 0
	s_add_u32 s82, s80, 0x5a00000
	v_writelane_b32 v233, s0, 62
	s_addc_u32 s83, s81, 0
	s_nop 0
	v_writelane_b32 v233, s1, 63
	s_add_u32 s0, s80, 0xd300000
	s_addc_u32 s1, s81, 0
	v_writelane_b32 v232, s0, 0
	s_nop 1
	v_writelane_b32 v232, s1, 1
	s_add_u32 s0, s80, 0xd500000
	v_writelane_b32 v232, s0, 2
	s_addc_u32 s0, s81, 0
	v_writelane_b32 v232, s0, 3
	s_add_u32 s0, s80, 0xd540000
	v_writelane_b32 v232, s0, 4
	s_addc_u32 s0, s81, 0
	v_writelane_b32 v232, s0, 5
	s_add_u32 s0, s80, 0x1000
	v_writelane_b32 v232, s0, 6
	s_addc_u32 s0, s81, 0
	v_writelane_b32 v232, s0, 7
	s_add_u32 s0, s80, 0x1800000
	v_writelane_b32 v232, s0, 8
	s_addc_u32 s0, s81, 0
	v_writelane_b32 v232, s0, 9
	s_add_u32 s0, s80, 0x2000
	v_writelane_b32 v232, s0, 10
	s_addc_u32 s0, s81, 0
	v_writelane_b32 v232, s0, 11
	s_add_u32 s0, s80, 0x1400000
	v_writelane_b32 v232, s0, 12
	s_addc_u32 s0, s81, 0
	v_writelane_b32 v232, s0, 13
	s_lshl_b32 s0, s74, 2
	v_writelane_b32 v232, s0, 14
	s_lshl_b32 s0, s60, 2
	v_writelane_b32 v232, s0, 15
	s_mov_b64 s[0:1], -1
	v_writelane_b32 v232, s0, 16
	s_nop 1
	v_writelane_b32 v232, s1, 17
	v_writelane_b32 v232, s48, 18
	s_nop 1
	v_writelane_b32 v232, s49, 19
	v_writelane_b32 v232, s50, 20
	v_writelane_b32 v232, s51, 21
	v_writelane_b32 v232, s52, 22
	v_writelane_b32 v232, s54, 23
	s_nop 1
	v_writelane_b32 v232, s55, 24
	v_writelane_b32 v232, s58, 25
	s_nop 1
	v_writelane_b32 v232, s59, 26
	v_writelane_b32 v232, s62, 27
	s_nop 1
	v_writelane_b32 v232, s63, 28
	v_writelane_b32 v232, s56, 29
	s_nop 1
	v_writelane_b32 v232, s57, 30
	v_writelane_b32 v232, s53, 31
	v_writelane_b32 v232, s61, 32
	v_writelane_b32 v232, s26, 33
	s_nop 1
	v_writelane_b32 v232, s27, 34
	v_writelane_b32 v232, s38, 35
	s_nop 1
	v_writelane_b32 v232, s39, 36
	v_writelane_b32 v232, s44, 37
	s_nop 1
	v_writelane_b32 v232, s45, 38
	s_mov_b32 s0, 0
	s_nop 1
	v_writelane_b32 v232, s0, 60
	s_branch .LBB0_171

.LBB0_1007:
	s_waitcnt vmcnt(0)
	s_movk_i32 s3, 0x4000
	s_barrier
	s_mov_b64 s[0:1], exec
	v_readlane_b32 s4, v234, 0
	v_readlane_b32 s5, v234, 1
	s_and_b64 s[4:5], s[0:1], s[4:5]
	v_readlane_b32 s53, v232, 31
	v_readlane_b32 s61, v232, 32
	s_mov_b64 exec, s[4:5]
	s_cbranch_execz .LBB0_1055
	v_readlane_b32 s6, v232, 60
	s_nop 3
	s_cmp_lg_u32 s6, 0
	s_cbranch_scc1 .Lgba_known
	v_readlane_b32 s4, v232, 14
	s_nop 3
	s_and_b32 s4, s4, 28
	s_lshl_b32 s4, s4, 6
	s_add_u32 s4, s4, 0x4c40
	s_add_u32 s4, s80, s4
	s_addc_u32 s5, s81, 0
	s_nop 0
	global_load_dword v3, v1, s[4:5] sc1
	s_waitcnt vmcnt(0)
	v_readfirstlane_b32 s6, v3
	s_nop 3
	s_bcnt1_i32_b32 s6, s6
	s_cmp_eq_u32 s6, 1
	s_cselect_b32 s6, 1, 2
	s_nop 1
	v_writelane_b32 v232, s6, 60
.Lgba_known:
	s_cmp_eq_u32 s6, 1
	s_cbranch_scc1 .Lgba_nowb
	buffer_wbl2 sc1
.Lgba_nowb:
	s_waitcnt vmcnt(0) lgkmcnt(0)
	v_readlane_b32 s4, v232, 14
	s_nop 3
	s_and_b32 s4, s4, 28
	s_lshl_b32 s4, s4, 6
	s_add_u32 s4, s4, 0x4c00
	s_add_u32 s4, s80, s4
	s_addc_u32 s5, s81, 0
	s_nop 0
	global_atomic_add v3, v1, v160, s[4:5] sc0
	s_waitcnt vmcnt(0)
	v_readfirstlane_b32 s6, v3
	s_nop 3
	s_lshr_b32 s7, s6, 6
	s_and_b32 s6, s6, 63
	s_cmp_eq_u32 s6, 63
	s_cbranch_scc0 .Lgba_wait
	global_atomic_add v1, v160, s[4:5] offset:128
	s_branch .Lgba_done
.Lgba_wait:
	s_mov_b32 s8, 0
.Lgba_spin:
	s_sleep 1
	global_load_dword v3, v1, s[4:5] offset:128 sc1
	s_waitcnt vmcnt(0)
	v_readfirstlane_b32 s6, v3
	s_nop 3
	s_cmp_lg_u32 s6, s7
	s_cbranch_scc1 .Lgba_done
	s_add_u32 s8, s8, 1
	s_cmp_lt_u32 s8, 0x8000
	s_cbranch_scc1 .Lgba_spin
.Lgba_done:
	s_waitcnt vmcnt(0)
	buffer_inv sc1
	s_waitcnt vmcnt(0)
.LBB0_1055:
	s_or_b64 exec, exec, s[0:1]
	v_mov_b32_e32 v0, v156
	s_waitcnt lgkmcnt(0)
	v_mov_b32_e32 v2, v156
	s_barrier
	v_readlane_b32 s0, v232, 14
	v_ashrrev_i32_e32 v2, 6, v2
	s_nop 3
	s_lshr_b32 s1, s0, 5
	s_and_b32 s0, s0, 28
	s_lshl_b32 s0, s0, 9
	s_lshl_b32 s1, s1, 5
	s_or_b32 s0, s0, s1
	s_nop 0
	v_add_u32_e32 v6, s0, v2
	v_cmp_gt_i32_e32 vcc, s3, v6
	s_and_saveexec_b64 s[4:5], vcc
	s_cbranch_execz .LBB0_1066
	v_lshlrev_b32_e32 v0, 2, v0
	v_and_b32_e32 v2, 0xfc, v0
	v_and_b32_e32 v0, 64, v170
	v_add_u32_e32 v0, 64, v0
	v_xor_b32_e32 v3, 32, v170
	v_cmp_lt_i32_e32 vcc, v3, v0
	s_lshl_b32 s86, s2, 10
	s_lshl_b64 s[0:1], s[86:87], 2
	v_cndmask_b32_e32 v3, v170, v3, vcc
	s_waitcnt vmcnt(0)
	v_lshlrev_b32_e32 v40, 2, v3
	v_xor_b32_e32 v3, 16, v170
	v_cmp_lt_i32_e32 vcc, v3, v0
	v_readlane_b32 s48, v234, 20
	s_add_u32 s6, s76, s0
	v_cndmask_b32_e32 v3, v170, v3, vcc
	v_lshlrev_b32_e32 v41, 2, v3
	v_xor_b32_e32 v3, 8, v170
	v_cmp_lt_i32_e32 vcc, v3, v0
	v_readlane_b32 s62, v234, 34
	v_readlane_b32 s63, v234, 35
	v_cndmask_b32_e32 v3, v170, v3, vcc
	v_lshlrev_b32_e32 v42, 2, v3
	v_xor_b32_e32 v3, 4, v170
	v_cmp_lt_i32_e32 vcc, v3, v0
	s_addc_u32 s7, s77, s1
	s_mov_b64 s[22:23], s[62:63]
	v_cndmask_b32_e32 v3, v170, v3, vcc
	v_lshlrev_b32_e32 v43, 2, v3
	v_xor_b32_e32 v3, 2, v170
	v_cmp_lt_i32_e32 vcc, v3, v0
	v_readlane_b32 s49, v234, 21
	s_add_u32 s0, s22, s0
	v_cndmask_b32_e32 v3, v170, v3, vcc
	v_lshlrev_b32_e32 v44, 2, v3
	v_xor_b32_e32 v3, 1, v170
	v_cmp_lt_i32_e32 vcc, v3, v0
	v_readlane_b32 s48, v232, 18
	s_addc_u32 s1, s23, s1
	v_cndmask_b32_e32 v0, v170, v3, vcc
	v_lshlrev_b32_e32 v45, 2, v0
	v_lshlrev_b32_e32 v0, 2, v2
	v_lshlrev_b32_e32 v2, 1, v2
	v_readlane_b32 s60, v234, 32
	v_readlane_b32 s61, v234, 33
	v_readlane_b32 s49, v232, 19
	v_lshl_add_u64 v[8:9], s[0:1], 0, v[0:1]
	v_lshl_add_u64 v[10:11], s[6:7], 0, v[0:1]
	v_lshl_add_u64 v[14:15], s[78:79], 0, v[0:1]
	v_or_b32_e32 v0, 0x200, v2
	v_readlane_b32 s54, v234, 26
	v_readlane_b32 s55, v234, 27
	v_readlane_b32 s56, v234, 28
	v_readlane_b32 s57, v234, 29
	v_readlane_b32 s58, v234, 30
	v_readlane_b32 s59, v234, 31
	v_readlane_b32 s60, v234, 38
	v_lshl_add_u64 v[16:17], s[48:49], 0, v[0:1]
	v_or_b32_e32 v0, 0x400, v2
	v_readlane_b32 s50, v234, 22
	v_readlane_b32 s51, v234, 23
	v_readlane_b32 s52, v234, 24
	v_readlane_b32 s53, v234, 25
	v_readlane_b32 s56, v232, 29
	v_readlane_b32 s54, v232, 23
	v_readlane_b32 s61, v234, 39
	v_readlane_b32 s62, v232, 27
	v_readlane_b32 s58, v232, 25
	v_mov_b32_e32 v3, v1
	v_lshl_add_u64 v[18:19], s[48:49], 0, v[0:1]
	v_or_b32_e32 v0, 0x600, v2
	v_readlane_b32 s53, v232, 31
	v_readlane_b32 s57, v232, 30
	v_readlane_b32 s55, v232, 24
	v_readlane_b32 s52, v232, 22
	v_readlane_b32 s51, v232, 21
	v_readlane_b32 s50, v232, 20
	v_readlane_b32 s61, v232, 32
	s_movk_i32 s19, 0x70
	v_readlane_b32 s63, v232, 28
	v_readlane_b32 s59, v232, 26
	v_lshl_add_u64 v[12:13], s[48:49], 0, v[2:3]
	v_lshl_add_u64 v[20:21], s[48:49], 0, v[0:1]
	s_mov_b64 s[6:7], 0
	s_branch .LBB0_1058
.LBB0_1057:
	v_add_u32_e32 v6, 4, v6
	v_and_b32_e32 v7, 31, v6
	v_cmp_gt_u32_e32 vcc, 4, v7
	s_or_b64 s[6:7], vcc, s[6:7]
	s_andn2_b64 exec, exec, s[6:7]
	s_cbranch_execz .LBB0_1066

.LBB0_1066:
	s_or_b64 exec, exec, s[4:5]
	v_readlane_b32 s0, v232, 16
	v_readlane_b32 s1, v232, 17
	s_andn2_b64 vcc, exec, s[0:1]
	s_mov_b64 s[0:1], -1
	s_cbranch_vccnz .LBB0_170
	s_waitcnt vmcnt(0)
	s_barrier
	s_mov_b64 s[0:1], exec
	v_readlane_b32 s4, v234, 0
	v_readlane_b32 s5, v234, 1
	s_and_b64 s[4:5], s[0:1], s[4:5]
	s_mov_b64 exec, s[4:5]
	s_cbranch_execz .LBB0_169
	v_readlane_b32 s6, v232, 60
	s_nop 3
	s_cmp_lg_u32 s6, 0
	s_cbranch_scc1 .Lgbb_known
	v_readlane_b32 s4, v232, 14
	s_nop 3
	s_and_b32 s4, s4, 28
	s_lshl_b32 s4, s4, 6
	s_add_u32 s4, s4, 0x4c40
	s_add_u32 s4, s80, s4
	s_addc_u32 s5, s81, 0
	s_nop 0
	global_load_dword v3, v1, s[4:5] sc1
	s_waitcnt vmcnt(0)
	v_readfirstlane_b32 s6, v3
	s_nop 3
	s_bcnt1_i32_b32 s6, s6
	s_cmp_eq_u32 s6, 1
	s_cselect_b32 s6, 1, 2
	s_nop 1
	v_writelane_b32 v232, s6, 60

.Lgbb_done:
	s_waitcnt vmcnt(0)
	buffer_inv sc1
	s_waitcnt vmcnt(0)
	s_branch .LBB0_169
